# scan: r,k,n,b staged as packed bf16 in LDS, expanded to per-lane f32 by one exact one-hot v_mfma_32x32x16_bf16 per step (2 ds_read_b128 per step instead of 5)
# speedup vs baseline: 1.0095x; 1.0095x over previous
; #define UFOR(v, n) _Pragma("unroll") for (int v = 0; v < (n); ++v)
; __device__ __forceinline__ float h2f(u16 u) { _Float16 h = __builtin_bit_cast(_Float16, u); return (float)h; }
; __device__ __forceinline__ void phase_scan(KP p) {
;     ...
;             UFOR(e, 2) {
;               const int q = pt + 128 * e, st = q >> 3, g8 = q & 7;
;               float f[8];
;               float* fd = feat + ((buf * 32 + st) * 5) * 64 + g8 * 8;
;               unpack8(rq[e][0], f); *(float4*)(fd) = make_float4(f[0], f[1], f[2], f[3]); *(float4*)(fd + 4) = make_float4(f[4], f[5], f[6], f[7]);
;               { const uint4 u = rq[e][1];
;                 f[0] = h2f((u16)(u.x & 0xffff)); f[1] = h2f((u16)(u.x >> 16)); f[2] = h2f((u16)(u.y & 0xffff)); f[3] = h2f((u16)(u.y >> 16));
;                 f[4] = h2f((u16)(u.z & 0xffff)); f[5] = h2f((u16)(u.z >> 16)); f[6] = h2f((u16)(u.w & 0xffff)); f[7] = h2f((u16)(u.w >> 16));
;                 UFOR(x, 8) f[x] = __expf(-f[x]);
;                 *(float4*)(fd + 64) = make_float4(f[0], f[1], f[2], f[3]); *(float4*)(fd + 68) = make_float4(f[4], f[5], f[6], f[7]); }
;               unpack8(rq[e][2], f); *(float4*)(fd + 128) = make_float4(f[0], f[1], f[2], f[3]); *(float4*)(fd + 132) = make_float4(f[4], f[5], f[6], f[7]);
;               unpack8(rq[e][3], f); *(float4*)(fd + 192) = make_float4(-f[0], -f[1], -f[2], -f[3]); *(float4*)(fd + 196) = make_float4(-f[4], -f[5], -f[6], -f[7]);
;               unpack8(rq[e][4], f); *(float4*)(fd + 256) = make_float4(f[0], f[1], f[2], f[3]); *(float4*)(fd + 260) = make_float4(f[4], f[5], f[6], f[7]);
;               if ((g8 >> 1) == rg) {
;                 unpack8(rq[e][5], f);
;                 float* vd = vbuf + (buf * 16 + (g8 & 1) * 8) * 32 + st;
;                 UFOR(x, 8) vd[x * 32] = f[x];
;               }
;             }
.LBB0_756:
	s_and_saveexec_b64 s[50:51], vcc
	s_xor_b64 s[70:71], exec, s[50:51]
	s_cbranch_execz .LBB0_770
	v_xor_b32_e32 v48, s18, v111
	v_and_b32_e32 v48, 1, v48
	v_cmp_eq_u32_e64 s[50:51], 1, v48
	s_and_saveexec_b64 s[72:73], s[50:51]
	s_xor_b64 s[72:73], exec, s[72:73]
	s_cbranch_execz .LBB0_766
	s_cmpk_eq_i32 s18, 0x207
	s_cbranch_scc1 .LBB0_764
	s_waitcnt vmcnt(0)
	v_and_b32_e32 v56, 7, v135
	v_bfe_u32 v57, v135, 3, 4
	v_bfe_u32 v58, v135, 7, 1
	v_lshl_add_u32 v57, v58, 5, v57
	v_mul_u32_u24_e32 v57, 0x220, v57
	v_lshrrev_b32_e32 v58, 2, v56
	v_and_b32_e32 v56, 3, v56
	v_lshlrev_b32_e32 v58, 4, v58
	v_lshl_add_u32 v56, v56, 2, v58
	s_mov_b32 s74, 0x16000
	v_add3_u32 v64, v57, v56, s74
	v_add_u32_e32 v65, 0x2200, v64
	s_mov_b32 s74, 0x5040100
	s_mov_b32 s75, 0x7060302
	v_perm_b32 v60, v6, v4, s74
	v_perm_b32 v61, v6, v4, s75
	v_perm_b32 v62, v7, v5, s74
	v_perm_b32 v63, v7, v5, s75
	ds_write2_b32 v64, v60, v61 offset0:0 offset1:8
	ds_write2_b32 v64, v62, v63 offset0:16 offset1:24
	v_perm_b32 v60, v10, v8, s74
	v_perm_b32 v61, v10, v8, s75
	v_perm_b32 v62, v11, v9, s74
	v_perm_b32 v63, v11, v9, s75
	ds_write2_b32 v64, v60, v61 offset0:32 offset1:40
	ds_write2_b32 v64, v62, v63 offset0:48 offset1:56
	v_perm_b32 v60, v14, v12, s74
	v_perm_b32 v61, v14, v12, s75
	v_perm_b32 v62, v15, v13, s74
	v_perm_b32 v63, v15, v13, s75
	v_xor_b32_e32 v60, 0x80008000, v60
	v_xor_b32_e32 v61, 0x80008000, v61
	v_xor_b32_e32 v62, 0x80008000, v62
	v_xor_b32_e32 v63, 0x80008000, v63
	ds_write2_b32 v64, v60, v61 offset0:64 offset1:72
	ds_write2_b32 v64, v62, v63 offset0:80 offset1:88
	v_perm_b32 v60, v18, v16, s74
	v_perm_b32 v61, v18, v16, s75
	v_perm_b32 v62, v19, v17, s74
	v_perm_b32 v63, v19, v17, s75
	ds_write2_b32 v64, v60, v61 offset0:96 offset1:104
	ds_write2_b32 v64, v62, v63 offset0:112 offset1:120
	v_cvt_f32_f16_e32 v48, v0
	v_cvt_f32_f16_sdwa v49, v0 dst_sel:DWORD dst_unused:UNUSED_PAD src0_sel:WORD_1
	v_cvt_f32_f16_e32 v50, v1
	v_cvt_f32_f16_sdwa v51, v1 dst_sel:DWORD dst_unused:UNUSED_PAD src0_sel:WORD_1
	v_cvt_f32_f16_e32 v52, v2
	v_cvt_f32_f16_sdwa v53, v2 dst_sel:DWORD dst_unused:UNUSED_PAD src0_sel:WORD_1
	v_cvt_f32_f16_e32 v54, v3
	v_cvt_f32_f16_sdwa v55, v3 dst_sel:DWORD dst_unused:UNUSED_PAD src0_sel:WORD_1
	v_mul_f32_e32 v48, 0xbfb8aa3b, v48
	v_mul_f32_e32 v49, 0xbfb8aa3b, v49
	v_mul_f32_e32 v50, 0xbfb8aa3b, v50
	v_mul_f32_e32 v51, 0xbfb8aa3b, v51
	v_exp_f32_e32 v48, v48
	v_exp_f32_e32 v49, v49
	v_exp_f32_e32 v50, v50
	v_exp_f32_e32 v51, v51
	v_mul_f32_e32 v52, 0xbfb8aa3b, v52
	v_mul_f32_e32 v53, 0xbfb8aa3b, v53
	v_mul_f32_e32 v54, 0xbfb8aa3b, v54
	v_mul_f32_e32 v55, 0xbfb8aa3b, v55
	v_exp_f32_e32 v52, v52
	v_exp_f32_e32 v53, v53
	v_exp_f32_e32 v54, v54
	v_exp_f32_e32 v55, v55
	ds_write_b128 v149, v[48:51] offset:256
	ds_write_b128 v149, v[52:55] offset:272
	s_and_saveexec_b64 s[50:51], s[48:49]
	s_cbranch_execz .LBB0_761
	v_lshlrev_b32_e32 v48, 16, v20
	v_and_b32_e32 v49, 0xffff0000, v20
	v_lshlrev_b32_e32 v50, 16, v21
	v_and_b32_e32 v51, 0xffff0000, v21
	v_lshlrev_b32_e32 v52, 16, v22
	v_and_b32_e32 v53, 0xffff0000, v22
	v_lshlrev_b32_e32 v54, 16, v23
	v_and_b32_e32 v55, 0xffff0000, v23
	ds_write2_b32 v130, v48, v49 offset1:32
	ds_write2_b32 v130, v50, v51 offset0:64 offset1:96
	ds_write2_b32 v130, v52, v53 offset0:128 offset1:160
	ds_write2_b32 v130, v54, v55 offset0:192 offset1:224
.LBB0_761:
	s_or_b64 exec, exec, s[50:51]
	v_perm_b32 v60, v26, v24, s74
	v_perm_b32 v61, v26, v24, s75
	v_perm_b32 v62, v27, v25, s74
	v_perm_b32 v63, v27, v25, s75
	ds_write2_b32 v65, v60, v61 offset0:0 offset1:8
	ds_write2_b32 v65, v62, v63 offset0:16 offset1:24
	v_perm_b32 v60, v34, v32, s74
	v_perm_b32 v61, v34, v32, s75
	v_perm_b32 v62, v35, v33, s74
	v_perm_b32 v63, v35, v33, s75
	ds_write2_b32 v65, v60, v61 offset0:32 offset1:40
	ds_write2_b32 v65, v62, v63 offset0:48 offset1:56
	v_perm_b32 v60, v38, v36, s74
	v_perm_b32 v61, v38, v36, s75
	v_perm_b32 v62, v39, v37, s74
	v_perm_b32 v63, v39, v37, s75
	v_xor_b32_e32 v60, 0x80008000, v60
	v_xor_b32_e32 v61, 0x80008000, v61
	v_xor_b32_e32 v62, 0x80008000, v62
	v_xor_b32_e32 v63, 0x80008000, v63
	ds_write2_b32 v65, v60, v61 offset0:64 offset1:72
	ds_write2_b32 v65, v62, v63 offset0:80 offset1:88
	v_perm_b32 v60, v42, v40, s74
	v_perm_b32 v61, v42, v40, s75
	v_perm_b32 v62, v43, v41, s74
	v_perm_b32 v63, v43, v41, s75
	ds_write2_b32 v65, v60, v61 offset0:96 offset1:104
	ds_write2_b32 v65, v62, v63 offset0:112 offset1:120
	v_cvt_f32_f16_e32 v48, v28
	v_cvt_f32_f16_sdwa v49, v28 dst_sel:DWORD dst_unused:UNUSED_PAD src0_sel:WORD_1
	v_cvt_f32_f16_e32 v50, v29
	v_cvt_f32_f16_sdwa v51, v29 dst_sel:DWORD dst_unused:UNUSED_PAD src0_sel:WORD_1
	v_cvt_f32_f16_e32 v52, v30
	v_cvt_f32_f16_sdwa v53, v30 dst_sel:DWORD dst_unused:UNUSED_PAD src0_sel:WORD_1
	v_cvt_f32_f16_e32 v54, v31
	v_cvt_f32_f16_sdwa v55, v31 dst_sel:DWORD dst_unused:UNUSED_PAD src0_sel:WORD_1
	v_mul_f32_e32 v48, 0xbfb8aa3b, v48
	v_mul_f32_e32 v49, 0xbfb8aa3b, v49
	v_mul_f32_e32 v50, 0xbfb8aa3b, v50
	v_mul_f32_e32 v51, 0xbfb8aa3b, v51
	v_exp_f32_e32 v48, v48
	v_exp_f32_e32 v49, v49
	v_exp_f32_e32 v50, v50
	v_exp_f32_e32 v51, v51
	v_mul_f32_e32 v52, 0xbfb8aa3b, v52
	v_mul_f32_e32 v53, 0xbfb8aa3b, v53
	v_mul_f32_e32 v54, 0xbfb8aa3b, v54
	v_mul_f32_e32 v55, 0xbfb8aa3b, v55
	v_exp_f32_e32 v52, v52
	v_exp_f32_e32 v53, v53
	v_exp_f32_e32 v54, v54
	v_exp_f32_e32 v55, v55
	ds_write_b128 v150, v[48:51] offset:256
	ds_write_b128 v150, v[52:55] offset:272
	s_and_saveexec_b64 s[50:51], s[48:49]
	s_cbranch_execz .LBB0_763
	v_lshlrev_b32_e32 v48, 16, v44
	v_and_b32_e32 v49, 0xffff0000, v44
	v_lshlrev_b32_e32 v50, 16, v45
	v_and_b32_e32 v51, 0xffff0000, v45
	v_lshlrev_b32_e32 v52, 16, v46
	v_and_b32_e32 v53, 0xffff0000, v46
	v_lshlrev_b32_e32 v54, 16, v47
	v_and_b32_e32 v55, 0xffff0000, v47
	ds_write2_b32 v130, v48, v49 offset0:16 offset1:48
	ds_write2_b32 v130, v50, v51 offset0:80 offset1:112
	ds_write2_b32 v130, v52, v53 offset0:144 offset1:176
	ds_write2_b32 v130, v54, v55 offset0:208 offset1:240

; #define YRED4(dst) { \
;           float a0 = b3 ? p2 : p0, a1 = b3 ? p3 : p1; const float s0 = b3 ? p0 : p2, s1 = b3 ? p1 : p3; \
;           a0 += dppf<0x128>(s0); a1 += dppf<0x128>(s1); \
;           float cc = b2 ? a1 : a0; const float dd = b2 ? a0 : a1; \
;           cc += dppf<0x141>(dd); cc += dppf<0xB1>(cc); cc += dppf<0x4E>(cc); dst = cc; }
; __device__ __forceinline__ void phase_scan(KP p) {
;     ...
;         const int buf = c & 1;
;         const float* fbase = feat + (buf * 32) * 320 + cs * 4;
;         const float* vb4 = vbuf + (buf * 16 + rowl) * 32;
;         const bool b3 = (cs & 8) != 0, b2 = (cs & 4) != 0;
;         float* yb = ybuf + (buf * 32 + (b3 ? 2 : 0) + (b2 ? 1 : 0)) * 16 + rowl;
;         float4 Ar, Aw, Ak, An, Ab, Br, Bw, Bk, Bn, Bb, Cr, Cw, Ck, Cn, Cb, Dr, Dw, Dk, Dn, Db;
;         float4 vcur = *(const float4*)vb4, vnext;
;         float q0 = 0.f, q1 = 0.f, q2 = 0.f, q3 = 0.f, p0 = 0.f, p1 = 0.f, p2 = 0.f, p3 = 0.f;
;     ...
;         SLD(A, 0); SLD(B, 1);
;         for (int g = 0; g < 8; ++g) {
;           const int st = g * 4;
;           SLD(C, st + 2); vnext = *(const float4*)(vb4 + st + 4);
;           __builtin_amdgcn_sched_barrier(0);
;           if (g > 0) { float yv; YRED4(yv); yb[(st - 4) * 16] = yv; }
;           SCOMP(A, vcur.x, q0);
;           SLD(D, st + 3);
;           __builtin_amdgcn_sched_barrier(0);
;           SCOMP(B, vcur.y, q1);
;           SLD(A, st + 4);
;           __builtin_amdgcn_sched_barrier(0);
;           SCOMP(C, vcur.z, q2);
;           SLD(B, st + 5);
;           __builtin_amdgcn_sched_barrier(0);
;           SCOMP(D, vcur.w, q3);
;           vcur = vnext; p0 = q0; p1 = q1; p2 = q2; p3 = q3;
;         }
.LBB0_770:
	s_or_saveexec_b64 s[50:51], s[70:71]
	s_movk_i32 s71, 0x600
	s_xor_b64 exec, exec, s[50:51]
	s_cbranch_execz .LBB0_755
	s_cmp_lt_i32 s18, 0
	s_cbranch_scc1 .LBB0_755
	s_and_b32 s70, s18, 1
	s_mul_i32 s19, s70, 0xa000
	v_lshl_add_u32 v106, s70, 11, v121
	v_add_u32_e32 v105, s19, v120
	v_lshl_add_u32 v107, s70, 11, v146
	v_and_b32_e32 v93, 63, v135
	v_bfe_u32 v94, v93, 3, 2
	v_and_b32_e32 v95, 3, v93
	v_lshl_add_u32 v94, v94, 2, v95
	v_lshrrev_b32_e32 v95, 5, v93
	v_lshl_add_u32 v94, v94, 1, v95
	s_mul_i32 s19, s70, 0x4400
	s_add_i32 s19, s19, 0x16000
	v_lshl_add_u32 v128, v94, 4, s19
	ds_read_b128 v[80:83], v106
	ds_read_b128 v[108:111], v128
	ds_read_b128 v[112:115], v128 offset:544
	ds_read_b128 v[16:19], v105 offset:256
	ds_read_b128 v[36:39], v105 offset:1536
	v_and_b32_e32 v94, 15, v93
	v_lshlrev_b32_e32 v95, 3, v95
	v_sub_u32_e32 v94, v94, v95
	v_and_b32_e32 v95, 1, v94
	v_lshlrev_b32_e32 v95, 4, v95
	v_mov_b32_e32 v93, 0x3f80
	v_lshlrev_b32_e32 v93, v95, v93
	v_lshrrev_b32_e32 v94, 1, v94
	v_cmp_eq_u32_e64 s[74:75], 0, v94
	s_nop 1
	v_cndmask_b32_e64 v124, 0, v93, s[74:75]
	v_cmp_eq_u32_e64 s[74:75], 1, v94
	s_nop 1
	v_cndmask_b32_e64 v125, 0, v93, s[74:75]
	v_cmp_eq_u32_e64 s[74:75], 2, v94
	s_nop 1
	v_cndmask_b32_e64 v126, 0, v93, s[74:75]
	v_cmp_eq_u32_e64 s[74:75], 3, v94
	s_nop 1
	v_cndmask_b32_e64 v127, 0, v93, s[74:75]
	s_nop 1
	s_waitcnt lgkmcnt(3)
	v_mfma_f32_32x32x16_bf16 v[0:15], v[108:111], v[124:127], 0
	s_waitcnt lgkmcnt(2)
	v_mfma_f32_32x32x16_bf16 v[20:35], v[112:115], v[124:127], 0
	ds_read_b128 v[108:111], v128 offset:1088
	s_nop 7
	s_nop 3
	s_waitcnt lgkmcnt(2)
	v_pk_mul_f32 v[84:85], v[116:117], v[8:9]
	v_pk_mul_f32 v[86:87], v[80:81], v[4:5] op_sel_hi:[0,1]
	v_pk_fma_f32 v[84:85], v[118:119], v[10:11], v[84:85]
	v_pk_mul_f32 v[88:89], v[80:81], v[6:7] op_sel_hi:[0,1]
	v_add_f32_e32 v92, v84, v85
	v_pk_fma_f32 v[86:87], v[116:117], v[16:17], v[86:87]
	ds_read_b128 v[112:115], v128 offset:1632
	v_add_f32_dpp v92, v92, v92 quad_perm:[1,0,3,2] row_mask:0xf bank_mask:0xf bound_ctrl:1
	v_pk_fma_f32 v[88:89], v[118:119], v[18:19], v[88:89]
	s_waitcnt lgkmcnt(1)
	v_mfma_f32_32x32x16_bf16 v[40:55], v[108:111], v[124:127], 0
	v_add_f32_dpp v92, v92, v92 quad_perm:[2,3,0,1] row_mask:0xf bank_mask:0xf bound_ctrl:1
	s_nop 1
	v_add_f32_dpp v92, v92, v92 row_half_mirror row_mask:0xf bank_mask:0xf bound_ctrl:1
	ds_read_b128 v[56:59], v105 offset:2816
	s_nop 0
	v_add_f32_dpp v92, v92, v92 row_mirror row_mask:0xf bank_mask:0xf bound_ctrl:1
	v_pk_fma_f32 v[116:117], v[12:13], v[92:93], v[86:87] op_sel_hi:[1,0,1]
	v_pk_fma_f32 v[118:119], v[14:15], v[92:93], v[88:89] op_sel_hi:[1,0,1]
	v_pk_mul_f32 v[84:85], v[116:117], v[28:29]
	v_pk_mul_f32 v[86:87], v[80:81], v[24:25] op_sel:[1,0]
	v_pk_fma_f32 v[84:85], v[118:119], v[30:31], v[84:85]
	v_pk_mul_f32 v[88:89], v[80:81], v[26:27] op_sel:[1,0]
	v_add_f32_e32 v92, v84, v85
	v_pk_fma_f32 v[86:87], v[116:117], v[36:37], v[86:87]
	v_pk_mul_f32 v[90:91], v[116:117], v[0:1]
	ds_read_b128 v[108:111], v128 offset:2176
	v_add_f32_dpp v92, v92, v92 quad_perm:[1,0,3,2] row_mask:0xf bank_mask:0xf bound_ctrl:1
	v_pk_fma_f32 v[88:89], v[118:119], v[38:39], v[88:89]
	v_pk_fma_f32 v[90:91], v[118:119], v[2:3], v[90:91]
	s_waitcnt lgkmcnt(2)
	v_mfma_f32_32x32x16_bf16 v[60:75], v[112:115], v[124:127], 0
	v_add_f32_dpp v92, v92, v92 quad_perm:[2,3,0,1] row_mask:0xf bank_mask:0xf bound_ctrl:1
	v_add_f32_e32 v96, v90, v91
	s_nop 0
	v_add_f32_dpp v92, v92, v92 row_half_mirror row_mask:0xf bank_mask:0xf bound_ctrl:1
	ds_read_b128 v[76:79], v105 offset:4096
	s_nop 0
	v_add_f32_dpp v92, v92, v92 row_mirror row_mask:0xf bank_mask:0xf bound_ctrl:1
	v_pk_fma_f32 v[116:117], v[32:33], v[92:93], v[86:87] op_sel_hi:[1,0,1]
	v_pk_fma_f32 v[118:119], v[34:35], v[92:93], v[88:89] op_sel_hi:[1,0,1]
	s_waitcnt lgkmcnt(2)
	v_pk_mul_f32 v[84:85], v[116:117], v[48:49]
	v_pk_mul_f32 v[86:87], v[82:83], v[44:45] op_sel_hi:[0,1]
	v_pk_fma_f32 v[84:85], v[118:119], v[50:51], v[84:85]
	v_pk_mul_f32 v[88:89], v[82:83], v[46:47] op_sel_hi:[0,1]
	v_add_f32_e32 v92, v84, v85
	v_pk_fma_f32 v[86:87], v[116:117], v[56:57], v[86:87]
	v_pk_mul_f32 v[90:91], v[116:117], v[20:21]
	ds_read_b128 v[112:115], v128 offset:2720
	v_add_f32_dpp v92, v92, v92 quad_perm:[1,0,3,2] row_mask:0xf bank_mask:0xf bound_ctrl:1
	v_pk_fma_f32 v[88:89], v[118:119], v[58:59], v[88:89]
	v_pk_fma_f32 v[90:91], v[118:119], v[22:23], v[90:91]
	s_waitcnt lgkmcnt(2)
	v_mfma_f32_32x32x16_bf16 v[0:15], v[108:111], v[124:127], 0
	v_add_f32_dpp v92, v92, v92 quad_perm:[2,3,0,1] row_mask:0xf bank_mask:0xf bound_ctrl:1
	v_add_f32_e32 v97, v90, v91
	s_nop 0
	v_add_f32_dpp v92, v92, v92 row_half_mirror row_mask:0xf bank_mask:0xf bound_ctrl:1
	ds_read_b128 v[16:19], v105 offset:5376
	s_nop 0
	v_add_f32_dpp v92, v92, v92 row_mirror row_mask:0xf bank_mask:0xf bound_ctrl:1
	v_pk_fma_f32 v[116:117], v[52:53], v[92:93], v[86:87] op_sel_hi:[1,0,1]
	v_pk_fma_f32 v[118:119], v[54:55], v[92:93], v[88:89] op_sel_hi:[1,0,1]
	s_waitcnt lgkmcnt(2)
	v_pk_mul_f32 v[84:85], v[116:117], v[68:69]
	v_pk_mul_f32 v[86:87], v[82:83], v[64:65] op_sel:[1,0]
	v_pk_fma_f32 v[84:85], v[118:119], v[70:71], v[84:85]
	v_pk_mul_f32 v[88:89], v[82:83], v[66:67] op_sel:[1,0]
	ds_read_b128 v[80:83], v106 offset:16
	v_add_f32_e32 v92, v84, v85
	v_pk_fma_f32 v[86:87], v[116:117], v[76:77], v[86:87]
	v_pk_mul_f32 v[90:91], v[116:117], v[40:41]
	ds_read_b128 v[108:111], v128 offset:3264
	v_add_f32_dpp v92, v92, v92 quad_perm:[1,0,3,2] row_mask:0xf bank_mask:0xf bound_ctrl:1
	v_pk_fma_f32 v[88:89], v[118:119], v[78:79], v[88:89]
	v_pk_fma_f32 v[90:91], v[118:119], v[42:43], v[90:91]
	s_waitcnt lgkmcnt(3)
; #define YRED4(dst) { \
;           float a0 = b3 ? p2 : p0, a1 = b3 ? p3 : p1; const float s0 = b3 ? p0 : p2, s1 = b3 ? p1 : p3; \
;           a0 += dppf<0x128>(s0); a1 += dppf<0x128>(s1); \
;           float cc = b2 ? a1 : a0; const float dd = b2 ? a0 : a1; \
;           cc += dppf<0x141>(dd); cc += dppf<0xB1>(cc); cc += dppf<0x4E>(cc); dst = cc; }
; __device__ __forceinline__ void phase_scan(KP p) {
;     ...
;         for (int g = 0; g < 8; ++g) {
;           const int st = g * 4;
;           SLD(C, st + 2); vnext = *(const float4*)(vb4 + st + 4);
;           __builtin_amdgcn_sched_barrier(0);
;           if (g > 0) { float yv; YRED4(yv); yb[(st - 4) * 16] = yv; }
;           SCOMP(A, vcur.x, q0);
;           SLD(D, st + 3);
;           __builtin_amdgcn_sched_barrier(0);
;           SCOMP(B, vcur.y, q1);
;           SLD(A, st + 4);
;           __builtin_amdgcn_sched_barrier(0);
;           SCOMP(C, vcur.z, q2);
;           SLD(B, st + 5);
;           __builtin_amdgcn_sched_barrier(0);
;           SCOMP(D, vcur.w, q3);
;           vcur = vnext; p0 = q0; p1 = q1; p2 = q2; p3 = q3;
;         }
	v_mfma_f32_32x32x16_bf16 v[20:35], v[112:115], v[124:127], 0
	v_add_f32_dpp v92, v92, v92 quad_perm:[2,3,0,1] row_mask:0xf bank_mask:0xf bound_ctrl:1
	v_add_f32_e32 v98, v90, v91
	s_nop 0
	v_add_f32_dpp v92, v92, v92 row_half_mirror row_mask:0xf bank_mask:0xf bound_ctrl:1
	ds_read_b128 v[36:39], v105 offset:6656
	s_nop 0
	v_add_f32_dpp v92, v92, v92 row_mirror row_mask:0xf bank_mask:0xf bound_ctrl:1
	v_pk_fma_f32 v[116:117], v[72:73], v[92:93], v[86:87] op_sel_hi:[1,0,1]
	v_pk_fma_f32 v[118:119], v[74:75], v[92:93], v[88:89] op_sel_hi:[1,0,1]
	s_waitcnt lgkmcnt(2)
	v_pk_mul_f32 v[84:85], v[116:117], v[8:9]
	v_pk_mul_f32 v[86:87], v[80:81], v[4:5] op_sel_hi:[0,1]
	v_pk_fma_f32 v[84:85], v[118:119], v[10:11], v[84:85]
	v_pk_mul_f32 v[88:89], v[80:81], v[6:7] op_sel_hi:[0,1]
	v_add_f32_e32 v92, v84, v85
	v_pk_fma_f32 v[86:87], v[116:117], v[16:17], v[86:87]
	v_pk_mul_f32 v[90:91], v[116:117], v[60:61]
	ds_read_b128 v[112:115], v128 offset:3808
	v_add_f32_dpp v92, v92, v92 quad_perm:[1,0,3,2] row_mask:0xf bank_mask:0xf bound_ctrl:1
	v_pk_fma_f32 v[88:89], v[118:119], v[18:19], v[88:89]
	v_pk_fma_f32 v[90:91], v[118:119], v[62:63], v[90:91]
	s_waitcnt lgkmcnt(2)
	v_mfma_f32_32x32x16_bf16 v[40:55], v[108:111], v[124:127], 0
	v_add_f32_dpp v92, v92, v92 quad_perm:[2,3,0,1] row_mask:0xf bank_mask:0xf bound_ctrl:1
	v_add_f32_e32 v99, v90, v91
	v_cndmask_b32_e64 v100, v98, v96, s[38:39]
	v_cndmask_b32_e64 v102, v96, v98, s[38:39]
	v_cndmask_b32_e64 v101, v99, v97, s[38:39]
	v_cndmask_b32_e64 v103, v97, v99, s[38:39]
	v_add_f32_dpp v92, v92, v92 row_half_mirror row_mask:0xf bank_mask:0xf bound_ctrl:1
	ds_read_b128 v[56:59], v105 offset:7936
	s_nop 0
	v_add_f32_dpp v92, v92, v92 row_mirror row_mask:0xf bank_mask:0xf bound_ctrl:1
	v_pk_fma_f32 v[116:117], v[12:13], v[92:93], v[86:87] op_sel_hi:[1,0,1]
	v_pk_fma_f32 v[118:119], v[14:15], v[92:93], v[88:89] op_sel_hi:[1,0,1]
	s_waitcnt lgkmcnt(2)
	v_pk_mul_f32 v[84:85], v[116:117], v[28:29]
	v_pk_mul_f32 v[86:87], v[80:81], v[24:25] op_sel:[1,0]
	v_pk_fma_f32 v[84:85], v[118:119], v[30:31], v[84:85]
	v_pk_mul_f32 v[88:89], v[80:81], v[26:27] op_sel:[1,0]
	v_add_f32_e32 v92, v84, v85
	v_pk_fma_f32 v[86:87], v[116:117], v[36:37], v[86:87]
	v_pk_mul_f32 v[90:91], v[116:117], v[0:1]
	ds_read_b128 v[108:111], v128 offset:4352
	v_add_f32_dpp v92, v92, v92 quad_perm:[1,0,3,2] row_mask:0xf bank_mask:0xf bound_ctrl:1
	v_pk_fma_f32 v[88:89], v[118:119], v[38:39], v[88:89]
	v_pk_fma_f32 v[90:91], v[118:119], v[2:3], v[90:91]
	s_waitcnt lgkmcnt(2)
	v_mfma_f32_32x32x16_bf16 v[60:75], v[112:115], v[124:127], 0
	v_add_f32_dpp v92, v92, v92 quad_perm:[2,3,0,1] row_mask:0xf bank_mask:0xf bound_ctrl:1
	v_add_f32_e32 v96, v90, v91
	v_add_f32_dpp v102, v102, v100 row_ror:8 row_mask:0xf bank_mask:0xf bound_ctrl:1
	v_add_f32_dpp v103, v103, v101 row_ror:8 row_mask:0xf bank_mask:0xf bound_ctrl:1
	v_add_f32_dpp v92, v92, v92 row_half_mirror row_mask:0xf bank_mask:0xf bound_ctrl:1
	ds_read_b128 v[76:79], v105 offset:9216
	s_nop 0
	v_add_f32_dpp v92, v92, v92 row_mirror row_mask:0xf bank_mask:0xf bound_ctrl:1
	v_cndmask_b32_e64 v104, v103, v102, s[40:41]
	v_cndmask_b32_e64 v102, v102, v103, s[40:41]
	v_pk_fma_f32 v[116:117], v[32:33], v[92:93], v[86:87] op_sel_hi:[1,0,1]
	v_pk_fma_f32 v[118:119], v[34:35], v[92:93], v[88:89] op_sel_hi:[1,0,1]
	s_waitcnt lgkmcnt(2)
	v_pk_mul_f32 v[84:85], v[116:117], v[48:49]
	v_pk_mul_f32 v[86:87], v[82:83], v[44:45] op_sel_hi:[0,1]
	v_pk_fma_f32 v[84:85], v[118:119], v[50:51], v[84:85]
	v_pk_mul_f32 v[88:89], v[82:83], v[46:47] op_sel_hi:[0,1]
	v_add_f32_e32 v92, v84, v85
	v_pk_fma_f32 v[86:87], v[116:117], v[56:57], v[86:87]
	v_pk_mul_f32 v[90:91], v[116:117], v[20:21]
	ds_read_b128 v[112:115], v128 offset:4896
	v_add_f32_dpp v92, v92, v92 quad_perm:[1,0,3,2] row_mask:0xf bank_mask:0xf bound_ctrl:1
	v_pk_fma_f32 v[88:89], v[118:119], v[58:59], v[88:89]
	v_pk_fma_f32 v[90:91], v[118:119], v[22:23], v[90:91]
	s_waitcnt lgkmcnt(2)
	v_mfma_f32_32x32x16_bf16 v[0:15], v[108:111], v[124:127], 0
	v_add_f32_dpp v92, v92, v92 quad_perm:[2,3,0,1] row_mask:0xf bank_mask:0xf bound_ctrl:1
	v_add_f32_e32 v97, v90, v91
	v_add_f32_dpp v102, v102, v104 row_half_mirror row_mask:0xf bank_mask:0xf bound_ctrl:1
	v_add_f32_dpp v92, v92, v92 row_half_mirror row_mask:0xf bank_mask:0xf bound_ctrl:1
	ds_read_b128 v[16:19], v105 offset:10496
	s_nop 0
	v_add_f32_dpp v92, v92, v92 row_mirror row_mask:0xf bank_mask:0xf bound_ctrl:1
	v_add_f32_dpp v102, v102, v102 quad_perm:[1,0,3,2] row_mask:0xf bank_mask:0xf bound_ctrl:1
	v_pk_fma_f32 v[116:117], v[52:53], v[92:93], v[86:87] op_sel_hi:[1,0,1]
	v_pk_fma_f32 v[118:119], v[54:55], v[92:93], v[88:89] op_sel_hi:[1,0,1]
	s_waitcnt lgkmcnt(2)
	v_pk_mul_f32 v[84:85], v[116:117], v[68:69]
	v_pk_mul_f32 v[86:87], v[82:83], v[64:65] op_sel:[1,0]
	v_pk_fma_f32 v[84:85], v[118:119], v[70:71], v[84:85]
	v_pk_mul_f32 v[88:89], v[82:83], v[66:67] op_sel:[1,0]
	ds_read_b128 v[80:83], v106 offset:32
	v_add_f32_e32 v92, v84, v85
	v_pk_fma_f32 v[86:87], v[116:117], v[76:77], v[86:87]
	v_pk_mul_f32 v[90:91], v[116:117], v[40:41]
	ds_read_b128 v[108:111], v128 offset:5440
	v_add_f32_dpp v92, v92, v92 quad_perm:[1,0,3,2] row_mask:0xf bank_mask:0xf bound_ctrl:1
	v_pk_fma_f32 v[88:89], v[118:119], v[78:79], v[88:89]
	v_pk_fma_f32 v[90:91], v[118:119], v[42:43], v[90:91]
	s_waitcnt lgkmcnt(3)
; #define YRED4(dst) { \
;           float a0 = b3 ? p2 : p0, a1 = b3 ? p3 : p1; const float s0 = b3 ? p0 : p2, s1 = b3 ? p1 : p3; \
;           a0 += dppf<0x128>(s0); a1 += dppf<0x128>(s1); \
;           float cc = b2 ? a1 : a0; const float dd = b2 ? a0 : a1; \
;           cc += dppf<0x141>(dd); cc += dppf<0xB1>(cc); cc += dppf<0x4E>(cc); dst = cc; }
; __device__ __forceinline__ void phase_scan(KP p) {
;     ...
;         for (int g = 0; g < 8; ++g) {
;           const int st = g * 4;
;           SLD(C, st + 2); vnext = *(const float4*)(vb4 + st + 4);
;           __builtin_amdgcn_sched_barrier(0);
;           if (g > 0) { float yv; YRED4(yv); yb[(st - 4) * 16] = yv; }
;           SCOMP(A, vcur.x, q0);
;           SLD(D, st + 3);
;           __builtin_amdgcn_sched_barrier(0);
;           SCOMP(B, vcur.y, q1);
;           SLD(A, st + 4);
;           __builtin_amdgcn_sched_barrier(0);
;           SCOMP(C, vcur.z, q2);
;           SLD(B, st + 5);
;           __builtin_amdgcn_sched_barrier(0);
;           SCOMP(D, vcur.w, q3);
;           vcur = vnext; p0 = q0; p1 = q1; p2 = q2; p3 = q3;
;         }
	v_mfma_f32_32x32x16_bf16 v[20:35], v[112:115], v[124:127], 0
	v_add_f32_dpp v92, v92, v92 quad_perm:[2,3,0,1] row_mask:0xf bank_mask:0xf bound_ctrl:1
	v_add_f32_e32 v98, v90, v91
	v_add_f32_dpp v102, v102, v102 quad_perm:[2,3,0,1] row_mask:0xf bank_mask:0xf bound_ctrl:1
	v_add_f32_dpp v92, v92, v92 row_half_mirror row_mask:0xf bank_mask:0xf bound_ctrl:1
	ds_read_b128 v[36:39], v105 offset:11776
	s_nop 0
	v_add_f32_dpp v92, v92, v92 row_mirror row_mask:0xf bank_mask:0xf bound_ctrl:1
	ds_write_b32 v107, v102
	v_pk_fma_f32 v[116:117], v[72:73], v[92:93], v[86:87] op_sel_hi:[1,0,1]
	v_pk_fma_f32 v[118:119], v[74:75], v[92:93], v[88:89] op_sel_hi:[1,0,1]
	s_waitcnt lgkmcnt(3)
	v_pk_mul_f32 v[84:85], v[116:117], v[8:9]
	v_pk_mul_f32 v[86:87], v[80:81], v[4:5] op_sel_hi:[0,1]
	v_pk_fma_f32 v[84:85], v[118:119], v[10:11], v[84:85]
	v_pk_mul_f32 v[88:89], v[80:81], v[6:7] op_sel_hi:[0,1]
	v_add_f32_e32 v92, v84, v85
	v_pk_fma_f32 v[86:87], v[116:117], v[16:17], v[86:87]
	v_pk_mul_f32 v[90:91], v[116:117], v[60:61]
	ds_read_b128 v[112:115], v128 offset:5984
	v_add_f32_dpp v92, v92, v92 quad_perm:[1,0,3,2] row_mask:0xf bank_mask:0xf bound_ctrl:1
	v_pk_fma_f32 v[88:89], v[118:119], v[18:19], v[88:89]
	v_pk_fma_f32 v[90:91], v[118:119], v[62:63], v[90:91]
	s_waitcnt lgkmcnt(3)
	v_mfma_f32_32x32x16_bf16 v[40:55], v[108:111], v[124:127], 0
	v_add_f32_dpp v92, v92, v92 quad_perm:[2,3,0,1] row_mask:0xf bank_mask:0xf bound_ctrl:1
	v_add_f32_e32 v99, v90, v91
	v_cndmask_b32_e64 v100, v98, v96, s[38:39]
	v_cndmask_b32_e64 v102, v96, v98, s[38:39]
	v_cndmask_b32_e64 v101, v99, v97, s[38:39]
	v_cndmask_b32_e64 v103, v97, v99, s[38:39]
	v_add_f32_dpp v92, v92, v92 row_half_mirror row_mask:0xf bank_mask:0xf bound_ctrl:1
	ds_read_b128 v[56:59], v105 offset:13056
	s_nop 0
	v_add_f32_dpp v92, v92, v92 row_mirror row_mask:0xf bank_mask:0xf bound_ctrl:1
	v_pk_fma_f32 v[116:117], v[12:13], v[92:93], v[86:87] op_sel_hi:[1,0,1]
	v_pk_fma_f32 v[118:119], v[14:15], v[92:93], v[88:89] op_sel_hi:[1,0,1]
	s_waitcnt lgkmcnt(3)
	v_pk_mul_f32 v[84:85], v[116:117], v[28:29]
	v_pk_mul_f32 v[86:87], v[80:81], v[24:25] op_sel:[1,0]
	v_pk_fma_f32 v[84:85], v[118:119], v[30:31], v[84:85]
	v_pk_mul_f32 v[88:89], v[80:81], v[26:27] op_sel:[1,0]
	v_add_f32_e32 v92, v84, v85
	v_pk_fma_f32 v[86:87], v[116:117], v[36:37], v[86:87]
	v_pk_mul_f32 v[90:91], v[116:117], v[0:1]
	ds_read_b128 v[108:111], v128 offset:6528
	v_add_f32_dpp v92, v92, v92 quad_perm:[1,0,3,2] row_mask:0xf bank_mask:0xf bound_ctrl:1
	v_pk_fma_f32 v[88:89], v[118:119], v[38:39], v[88:89]
	v_pk_fma_f32 v[90:91], v[118:119], v[2:3], v[90:91]
	s_waitcnt lgkmcnt(2)
	v_mfma_f32_32x32x16_bf16 v[60:75], v[112:115], v[124:127], 0
	v_add_f32_dpp v92, v92, v92 quad_perm:[2,3,0,1] row_mask:0xf bank_mask:0xf bound_ctrl:1
	v_add_f32_e32 v96, v90, v91
	v_add_f32_dpp v102, v102, v100 row_ror:8 row_mask:0xf bank_mask:0xf bound_ctrl:1
	v_add_f32_dpp v103, v103, v101 row_ror:8 row_mask:0xf bank_mask:0xf bound_ctrl:1
	v_add_f32_dpp v92, v92, v92 row_half_mirror row_mask:0xf bank_mask:0xf bound_ctrl:1
	ds_read_b128 v[76:79], v105 offset:14336
	s_nop 0
	v_add_f32_dpp v92, v92, v92 row_mirror row_mask:0xf bank_mask:0xf bound_ctrl:1
	v_cndmask_b32_e64 v104, v103, v102, s[40:41]
	v_cndmask_b32_e64 v102, v102, v103, s[40:41]
	v_pk_fma_f32 v[116:117], v[32:33], v[92:93], v[86:87] op_sel_hi:[1,0,1]
	v_pk_fma_f32 v[118:119], v[34:35], v[92:93], v[88:89] op_sel_hi:[1,0,1]
	s_waitcnt lgkmcnt(2)
	v_pk_mul_f32 v[84:85], v[116:117], v[48:49]
	v_pk_mul_f32 v[86:87], v[82:83], v[44:45] op_sel_hi:[0,1]
	v_pk_fma_f32 v[84:85], v[118:119], v[50:51], v[84:85]
	v_pk_mul_f32 v[88:89], v[82:83], v[46:47] op_sel_hi:[0,1]
	v_add_f32_e32 v92, v84, v85
	v_pk_fma_f32 v[86:87], v[116:117], v[56:57], v[86:87]
	v_pk_mul_f32 v[90:91], v[116:117], v[20:21]
	ds_read_b128 v[112:115], v128 offset:7072
	v_add_f32_dpp v92, v92, v92 quad_perm:[1,0,3,2] row_mask:0xf bank_mask:0xf bound_ctrl:1
	v_pk_fma_f32 v[88:89], v[118:119], v[58:59], v[88:89]
	v_pk_fma_f32 v[90:91], v[118:119], v[22:23], v[90:91]
	s_waitcnt lgkmcnt(2)
	v_mfma_f32_32x32x16_bf16 v[0:15], v[108:111], v[124:127], 0
	v_add_f32_dpp v92, v92, v92 quad_perm:[2,3,0,1] row_mask:0xf bank_mask:0xf bound_ctrl:1
	v_add_f32_e32 v97, v90, v91
	v_add_f32_dpp v102, v102, v104 row_half_mirror row_mask:0xf bank_mask:0xf bound_ctrl:1
	v_add_f32_dpp v92, v92, v92 row_half_mirror row_mask:0xf bank_mask:0xf bound_ctrl:1
	ds_read_b128 v[16:19], v105 offset:15616
	s_nop 0
	v_add_f32_dpp v92, v92, v92 row_mirror row_mask:0xf bank_mask:0xf bound_ctrl:1
	v_add_f32_dpp v102, v102, v102 quad_perm:[1,0,3,2] row_mask:0xf bank_mask:0xf bound_ctrl:1
	v_pk_fma_f32 v[116:117], v[52:53], v[92:93], v[86:87] op_sel_hi:[1,0,1]
	v_pk_fma_f32 v[118:119], v[54:55], v[92:93], v[88:89] op_sel_hi:[1,0,1]
	s_waitcnt lgkmcnt(2)
	v_pk_mul_f32 v[84:85], v[116:117], v[68:69]
	v_pk_mul_f32 v[86:87], v[82:83], v[64:65] op_sel:[1,0]
	v_pk_fma_f32 v[84:85], v[118:119], v[70:71], v[84:85]
	v_pk_mul_f32 v[88:89], v[82:83], v[66:67] op_sel:[1,0]
	ds_read_b128 v[80:83], v106 offset:48
	v_add_f32_e32 v92, v84, v85
	v_pk_fma_f32 v[86:87], v[116:117], v[76:77], v[86:87]
	v_pk_mul_f32 v[90:91], v[116:117], v[40:41]
	ds_read_b128 v[108:111], v128 offset:7616
	v_add_f32_dpp v92, v92, v92 quad_perm:[1,0,3,2] row_mask:0xf bank_mask:0xf bound_ctrl:1
	v_pk_fma_f32 v[88:89], v[118:119], v[78:79], v[88:89]
	v_pk_fma_f32 v[90:91], v[118:119], v[42:43], v[90:91]
	s_waitcnt lgkmcnt(3)
; #define YRED4(dst) { \
;           float a0 = b3 ? p2 : p0, a1 = b3 ? p3 : p1; const float s0 = b3 ? p0 : p2, s1 = b3 ? p1 : p3; \
;           a0 += dppf<0x128>(s0); a1 += dppf<0x128>(s1); \
;           float cc = b2 ? a1 : a0; const float dd = b2 ? a0 : a1; \
;           cc += dppf<0x141>(dd); cc += dppf<0xB1>(cc); cc += dppf<0x4E>(cc); dst = cc; }
; __device__ __forceinline__ void phase_scan(KP p) {
;     ...
;         for (int g = 0; g < 8; ++g) {
;           const int st = g * 4;
;           SLD(C, st + 2); vnext = *(const float4*)(vb4 + st + 4);
;           __builtin_amdgcn_sched_barrier(0);
;           if (g > 0) { float yv; YRED4(yv); yb[(st - 4) * 16] = yv; }
;           SCOMP(A, vcur.x, q0);
;           SLD(D, st + 3);
;           __builtin_amdgcn_sched_barrier(0);
;           SCOMP(B, vcur.y, q1);
;           SLD(A, st + 4);
;           __builtin_amdgcn_sched_barrier(0);
;           SCOMP(C, vcur.z, q2);
;           SLD(B, st + 5);
;           __builtin_amdgcn_sched_barrier(0);
;           SCOMP(D, vcur.w, q3);
;           vcur = vnext; p0 = q0; p1 = q1; p2 = q2; p3 = q3;
;         }
	v_mfma_f32_32x32x16_bf16 v[20:35], v[112:115], v[124:127], 0
	v_add_f32_dpp v92, v92, v92 quad_perm:[2,3,0,1] row_mask:0xf bank_mask:0xf bound_ctrl:1
	v_add_f32_e32 v98, v90, v91
	v_add_f32_dpp v102, v102, v102 quad_perm:[2,3,0,1] row_mask:0xf bank_mask:0xf bound_ctrl:1
	v_add_f32_dpp v92, v92, v92 row_half_mirror row_mask:0xf bank_mask:0xf bound_ctrl:1
	ds_read_b128 v[36:39], v105 offset:16896
	s_nop 0
	v_add_f32_dpp v92, v92, v92 row_mirror row_mask:0xf bank_mask:0xf bound_ctrl:1
	ds_write_b32 v107, v102 offset:256
	v_pk_fma_f32 v[116:117], v[72:73], v[92:93], v[86:87] op_sel_hi:[1,0,1]
	v_pk_fma_f32 v[118:119], v[74:75], v[92:93], v[88:89] op_sel_hi:[1,0,1]
	s_waitcnt lgkmcnt(3)
	v_pk_mul_f32 v[84:85], v[116:117], v[8:9]
	v_pk_mul_f32 v[86:87], v[80:81], v[4:5] op_sel_hi:[0,1]
	v_pk_fma_f32 v[84:85], v[118:119], v[10:11], v[84:85]
	v_pk_mul_f32 v[88:89], v[80:81], v[6:7] op_sel_hi:[0,1]
	v_add_f32_e32 v92, v84, v85
	v_pk_fma_f32 v[86:87], v[116:117], v[16:17], v[86:87]
	v_pk_mul_f32 v[90:91], v[116:117], v[60:61]
	ds_read_b128 v[112:115], v128 offset:8160
	v_add_f32_dpp v92, v92, v92 quad_perm:[1,0,3,2] row_mask:0xf bank_mask:0xf bound_ctrl:1
	v_pk_fma_f32 v[88:89], v[118:119], v[18:19], v[88:89]
	v_pk_fma_f32 v[90:91], v[118:119], v[62:63], v[90:91]
	s_waitcnt lgkmcnt(3)
	v_mfma_f32_32x32x16_bf16 v[40:55], v[108:111], v[124:127], 0
	v_add_f32_dpp v92, v92, v92 quad_perm:[2,3,0,1] row_mask:0xf bank_mask:0xf bound_ctrl:1
	v_add_f32_e32 v99, v90, v91
	v_cndmask_b32_e64 v100, v98, v96, s[38:39]
	v_cndmask_b32_e64 v102, v96, v98, s[38:39]
	v_cndmask_b32_e64 v101, v99, v97, s[38:39]
	v_cndmask_b32_e64 v103, v97, v99, s[38:39]
	v_add_f32_dpp v92, v92, v92 row_half_mirror row_mask:0xf bank_mask:0xf bound_ctrl:1
	ds_read_b128 v[56:59], v105 offset:18176
	s_nop 0
	v_add_f32_dpp v92, v92, v92 row_mirror row_mask:0xf bank_mask:0xf bound_ctrl:1
	v_pk_fma_f32 v[116:117], v[12:13], v[92:93], v[86:87] op_sel_hi:[1,0,1]
	v_pk_fma_f32 v[118:119], v[14:15], v[92:93], v[88:89] op_sel_hi:[1,0,1]
	s_waitcnt lgkmcnt(3)
	v_pk_mul_f32 v[84:85], v[116:117], v[28:29]
	v_pk_mul_f32 v[86:87], v[80:81], v[24:25] op_sel:[1,0]
	v_pk_fma_f32 v[84:85], v[118:119], v[30:31], v[84:85]
	v_pk_mul_f32 v[88:89], v[80:81], v[26:27] op_sel:[1,0]
	v_add_f32_e32 v92, v84, v85
	v_pk_fma_f32 v[86:87], v[116:117], v[36:37], v[86:87]
	v_pk_mul_f32 v[90:91], v[116:117], v[0:1]
	ds_read_b128 v[108:111], v128 offset:8704
	v_add_f32_dpp v92, v92, v92 quad_perm:[1,0,3,2] row_mask:0xf bank_mask:0xf bound_ctrl:1
	v_pk_fma_f32 v[88:89], v[118:119], v[38:39], v[88:89]
	v_pk_fma_f32 v[90:91], v[118:119], v[2:3], v[90:91]
	s_waitcnt lgkmcnt(2)
	v_mfma_f32_32x32x16_bf16 v[60:75], v[112:115], v[124:127], 0
	v_add_f32_dpp v92, v92, v92 quad_perm:[2,3,0,1] row_mask:0xf bank_mask:0xf bound_ctrl:1
	v_add_f32_e32 v96, v90, v91
	v_add_f32_dpp v102, v102, v100 row_ror:8 row_mask:0xf bank_mask:0xf bound_ctrl:1
	v_add_f32_dpp v103, v103, v101 row_ror:8 row_mask:0xf bank_mask:0xf bound_ctrl:1
	v_add_f32_dpp v92, v92, v92 row_half_mirror row_mask:0xf bank_mask:0xf bound_ctrl:1
	ds_read_b128 v[76:79], v105 offset:19456
	s_nop 0
	v_add_f32_dpp v92, v92, v92 row_mirror row_mask:0xf bank_mask:0xf bound_ctrl:1
	v_cndmask_b32_e64 v104, v103, v102, s[40:41]
	v_cndmask_b32_e64 v102, v102, v103, s[40:41]
	v_pk_fma_f32 v[116:117], v[32:33], v[92:93], v[86:87] op_sel_hi:[1,0,1]
	v_pk_fma_f32 v[118:119], v[34:35], v[92:93], v[88:89] op_sel_hi:[1,0,1]
	s_waitcnt lgkmcnt(2)
	v_pk_mul_f32 v[84:85], v[116:117], v[48:49]
	v_pk_mul_f32 v[86:87], v[82:83], v[44:45] op_sel_hi:[0,1]
	v_pk_fma_f32 v[84:85], v[118:119], v[50:51], v[84:85]
	v_pk_mul_f32 v[88:89], v[82:83], v[46:47] op_sel_hi:[0,1]
	v_add_f32_e32 v92, v84, v85
	v_pk_fma_f32 v[86:87], v[116:117], v[56:57], v[86:87]
	v_pk_mul_f32 v[90:91], v[116:117], v[20:21]
	ds_read_b128 v[112:115], v128 offset:9248
	v_add_f32_dpp v92, v92, v92 quad_perm:[1,0,3,2] row_mask:0xf bank_mask:0xf bound_ctrl:1
	v_pk_fma_f32 v[88:89], v[118:119], v[58:59], v[88:89]
	v_pk_fma_f32 v[90:91], v[118:119], v[22:23], v[90:91]
	s_waitcnt lgkmcnt(2)
	v_mfma_f32_32x32x16_bf16 v[0:15], v[108:111], v[124:127], 0
	v_add_f32_dpp v92, v92, v92 quad_perm:[2,3,0,1] row_mask:0xf bank_mask:0xf bound_ctrl:1
	v_add_f32_e32 v97, v90, v91
	v_add_f32_dpp v102, v102, v104 row_half_mirror row_mask:0xf bank_mask:0xf bound_ctrl:1
	v_add_f32_dpp v92, v92, v92 row_half_mirror row_mask:0xf bank_mask:0xf bound_ctrl:1
	ds_read_b128 v[16:19], v105 offset:20736
	s_nop 0
	v_add_f32_dpp v92, v92, v92 row_mirror row_mask:0xf bank_mask:0xf bound_ctrl:1
	v_add_f32_dpp v102, v102, v102 quad_perm:[1,0,3,2] row_mask:0xf bank_mask:0xf bound_ctrl:1
	v_pk_fma_f32 v[116:117], v[52:53], v[92:93], v[86:87] op_sel_hi:[1,0,1]
	v_pk_fma_f32 v[118:119], v[54:55], v[92:93], v[88:89] op_sel_hi:[1,0,1]
	s_waitcnt lgkmcnt(2)
	v_pk_mul_f32 v[84:85], v[116:117], v[68:69]
	v_pk_mul_f32 v[86:87], v[82:83], v[64:65] op_sel:[1,0]
	v_pk_fma_f32 v[84:85], v[118:119], v[70:71], v[84:85]
	v_pk_mul_f32 v[88:89], v[82:83], v[66:67] op_sel:[1,0]
	ds_read_b128 v[80:83], v106 offset:64
	v_add_f32_e32 v92, v84, v85
	v_pk_fma_f32 v[86:87], v[116:117], v[76:77], v[86:87]
	v_pk_mul_f32 v[90:91], v[116:117], v[40:41]
	ds_read_b128 v[108:111], v128 offset:9792
	v_add_f32_dpp v92, v92, v92 quad_perm:[1,0,3,2] row_mask:0xf bank_mask:0xf bound_ctrl:1
	v_pk_fma_f32 v[88:89], v[118:119], v[78:79], v[88:89]
	v_pk_fma_f32 v[90:91], v[118:119], v[42:43], v[90:91]
	s_waitcnt lgkmcnt(3)
; #define YRED4(dst) { \
;           float a0 = b3 ? p2 : p0, a1 = b3 ? p3 : p1; const float s0 = b3 ? p0 : p2, s1 = b3 ? p1 : p3; \
;           a0 += dppf<0x128>(s0); a1 += dppf<0x128>(s1); \
;           float cc = b2 ? a1 : a0; const float dd = b2 ? a0 : a1; \
;           cc += dppf<0x141>(dd); cc += dppf<0xB1>(cc); cc += dppf<0x4E>(cc); dst = cc; }
; __device__ __forceinline__ void phase_scan(KP p) {
;     ...
;         for (int g = 0; g < 8; ++g) {
;           const int st = g * 4;
;           SLD(C, st + 2); vnext = *(const float4*)(vb4 + st + 4);
;           __builtin_amdgcn_sched_barrier(0);
;           if (g > 0) { float yv; YRED4(yv); yb[(st - 4) * 16] = yv; }
;           SCOMP(A, vcur.x, q0);
;           SLD(D, st + 3);
;           __builtin_amdgcn_sched_barrier(0);
;           SCOMP(B, vcur.y, q1);
;           SLD(A, st + 4);
;           __builtin_amdgcn_sched_barrier(0);
;           SCOMP(C, vcur.z, q2);
;           SLD(B, st + 5);
;           __builtin_amdgcn_sched_barrier(0);
;           SCOMP(D, vcur.w, q3);
;           vcur = vnext; p0 = q0; p1 = q1; p2 = q2; p3 = q3;
;         }
	v_mfma_f32_32x32x16_bf16 v[20:35], v[112:115], v[124:127], 0
	v_add_f32_dpp v92, v92, v92 quad_perm:[2,3,0,1] row_mask:0xf bank_mask:0xf bound_ctrl:1
	v_add_f32_e32 v98, v90, v91
	v_add_f32_dpp v102, v102, v102 quad_perm:[2,3,0,1] row_mask:0xf bank_mask:0xf bound_ctrl:1
	v_add_f32_dpp v92, v92, v92 row_half_mirror row_mask:0xf bank_mask:0xf bound_ctrl:1
	ds_read_b128 v[36:39], v105 offset:22016
	s_nop 0
	v_add_f32_dpp v92, v92, v92 row_mirror row_mask:0xf bank_mask:0xf bound_ctrl:1
	ds_write_b32 v107, v102 offset:512
	v_pk_fma_f32 v[116:117], v[72:73], v[92:93], v[86:87] op_sel_hi:[1,0,1]
	v_pk_fma_f32 v[118:119], v[74:75], v[92:93], v[88:89] op_sel_hi:[1,0,1]
	s_waitcnt lgkmcnt(3)
	v_pk_mul_f32 v[84:85], v[116:117], v[8:9]
	v_pk_mul_f32 v[86:87], v[80:81], v[4:5] op_sel_hi:[0,1]
	v_pk_fma_f32 v[84:85], v[118:119], v[10:11], v[84:85]
	v_pk_mul_f32 v[88:89], v[80:81], v[6:7] op_sel_hi:[0,1]
	v_add_f32_e32 v92, v84, v85
	v_pk_fma_f32 v[86:87], v[116:117], v[16:17], v[86:87]
	v_pk_mul_f32 v[90:91], v[116:117], v[60:61]
	ds_read_b128 v[112:115], v128 offset:10336
	v_add_f32_dpp v92, v92, v92 quad_perm:[1,0,3,2] row_mask:0xf bank_mask:0xf bound_ctrl:1
	v_pk_fma_f32 v[88:89], v[118:119], v[18:19], v[88:89]
	v_pk_fma_f32 v[90:91], v[118:119], v[62:63], v[90:91]
	s_waitcnt lgkmcnt(3)
	v_mfma_f32_32x32x16_bf16 v[40:55], v[108:111], v[124:127], 0
	v_add_f32_dpp v92, v92, v92 quad_perm:[2,3,0,1] row_mask:0xf bank_mask:0xf bound_ctrl:1
	v_add_f32_e32 v99, v90, v91
	v_cndmask_b32_e64 v100, v98, v96, s[38:39]
	v_cndmask_b32_e64 v102, v96, v98, s[38:39]
	v_cndmask_b32_e64 v101, v99, v97, s[38:39]
	v_cndmask_b32_e64 v103, v97, v99, s[38:39]
	v_add_f32_dpp v92, v92, v92 row_half_mirror row_mask:0xf bank_mask:0xf bound_ctrl:1
	ds_read_b128 v[56:59], v105 offset:23296
	s_nop 0
	v_add_f32_dpp v92, v92, v92 row_mirror row_mask:0xf bank_mask:0xf bound_ctrl:1
	v_pk_fma_f32 v[116:117], v[12:13], v[92:93], v[86:87] op_sel_hi:[1,0,1]
	v_pk_fma_f32 v[118:119], v[14:15], v[92:93], v[88:89] op_sel_hi:[1,0,1]
	s_waitcnt lgkmcnt(3)
	v_pk_mul_f32 v[84:85], v[116:117], v[28:29]
	v_pk_mul_f32 v[86:87], v[80:81], v[24:25] op_sel:[1,0]
	v_pk_fma_f32 v[84:85], v[118:119], v[30:31], v[84:85]
	v_pk_mul_f32 v[88:89], v[80:81], v[26:27] op_sel:[1,0]
	v_add_f32_e32 v92, v84, v85
	v_pk_fma_f32 v[86:87], v[116:117], v[36:37], v[86:87]
	v_pk_mul_f32 v[90:91], v[116:117], v[0:1]
	ds_read_b128 v[108:111], v128 offset:10880
	v_add_f32_dpp v92, v92, v92 quad_perm:[1,0,3,2] row_mask:0xf bank_mask:0xf bound_ctrl:1
	v_pk_fma_f32 v[88:89], v[118:119], v[38:39], v[88:89]
	v_pk_fma_f32 v[90:91], v[118:119], v[2:3], v[90:91]
	s_waitcnt lgkmcnt(2)
	v_mfma_f32_32x32x16_bf16 v[60:75], v[112:115], v[124:127], 0
	v_add_f32_dpp v92, v92, v92 quad_perm:[2,3,0,1] row_mask:0xf bank_mask:0xf bound_ctrl:1
	v_add_f32_e32 v96, v90, v91
	v_add_f32_dpp v102, v102, v100 row_ror:8 row_mask:0xf bank_mask:0xf bound_ctrl:1
	v_add_f32_dpp v103, v103, v101 row_ror:8 row_mask:0xf bank_mask:0xf bound_ctrl:1
	v_add_f32_dpp v92, v92, v92 row_half_mirror row_mask:0xf bank_mask:0xf bound_ctrl:1
	ds_read_b128 v[76:79], v105 offset:24576
	s_nop 0
	v_add_f32_dpp v92, v92, v92 row_mirror row_mask:0xf bank_mask:0xf bound_ctrl:1
	v_cndmask_b32_e64 v104, v103, v102, s[40:41]
	v_cndmask_b32_e64 v102, v102, v103, s[40:41]
	v_pk_fma_f32 v[116:117], v[32:33], v[92:93], v[86:87] op_sel_hi:[1,0,1]
	v_pk_fma_f32 v[118:119], v[34:35], v[92:93], v[88:89] op_sel_hi:[1,0,1]
	s_waitcnt lgkmcnt(2)
	v_pk_mul_f32 v[84:85], v[116:117], v[48:49]
	v_pk_mul_f32 v[86:87], v[82:83], v[44:45] op_sel_hi:[0,1]
	v_pk_fma_f32 v[84:85], v[118:119], v[50:51], v[84:85]
	v_pk_mul_f32 v[88:89], v[82:83], v[46:47] op_sel_hi:[0,1]
	v_add_f32_e32 v92, v84, v85
	v_pk_fma_f32 v[86:87], v[116:117], v[56:57], v[86:87]
	v_pk_mul_f32 v[90:91], v[116:117], v[20:21]
	ds_read_b128 v[112:115], v128 offset:11424
	v_add_f32_dpp v92, v92, v92 quad_perm:[1,0,3,2] row_mask:0xf bank_mask:0xf bound_ctrl:1
	v_pk_fma_f32 v[88:89], v[118:119], v[58:59], v[88:89]
	v_pk_fma_f32 v[90:91], v[118:119], v[22:23], v[90:91]
	s_waitcnt lgkmcnt(2)
	v_mfma_f32_32x32x16_bf16 v[0:15], v[108:111], v[124:127], 0
	v_add_f32_dpp v92, v92, v92 quad_perm:[2,3,0,1] row_mask:0xf bank_mask:0xf bound_ctrl:1
	v_add_f32_e32 v97, v90, v91
	v_add_f32_dpp v102, v102, v104 row_half_mirror row_mask:0xf bank_mask:0xf bound_ctrl:1
	v_add_f32_dpp v92, v92, v92 row_half_mirror row_mask:0xf bank_mask:0xf bound_ctrl:1
	ds_read_b128 v[16:19], v105 offset:25856
	s_nop 0
	v_add_f32_dpp v92, v92, v92 row_mirror row_mask:0xf bank_mask:0xf bound_ctrl:1
	v_add_f32_dpp v102, v102, v102 quad_perm:[1,0,3,2] row_mask:0xf bank_mask:0xf bound_ctrl:1
	v_pk_fma_f32 v[116:117], v[52:53], v[92:93], v[86:87] op_sel_hi:[1,0,1]
	v_pk_fma_f32 v[118:119], v[54:55], v[92:93], v[88:89] op_sel_hi:[1,0,1]
	s_waitcnt lgkmcnt(2)
	v_pk_mul_f32 v[84:85], v[116:117], v[68:69]
	v_pk_mul_f32 v[86:87], v[82:83], v[64:65] op_sel:[1,0]
	v_pk_fma_f32 v[84:85], v[118:119], v[70:71], v[84:85]
	v_pk_mul_f32 v[88:89], v[82:83], v[66:67] op_sel:[1,0]
	ds_read_b128 v[80:83], v106 offset:80
	v_add_f32_e32 v92, v84, v85
	v_pk_fma_f32 v[86:87], v[116:117], v[76:77], v[86:87]
	v_pk_mul_f32 v[90:91], v[116:117], v[40:41]
	ds_read_b128 v[108:111], v128 offset:11968
	v_add_f32_dpp v92, v92, v92 quad_perm:[1,0,3,2] row_mask:0xf bank_mask:0xf bound_ctrl:1
	v_pk_fma_f32 v[88:89], v[118:119], v[78:79], v[88:89]
	v_pk_fma_f32 v[90:91], v[118:119], v[42:43], v[90:91]
	s_waitcnt lgkmcnt(3)
; #define YRED4(dst) { \
;           float a0 = b3 ? p2 : p0, a1 = b3 ? p3 : p1; const float s0 = b3 ? p0 : p2, s1 = b3 ? p1 : p3; \
;           a0 += dppf<0x128>(s0); a1 += dppf<0x128>(s1); \
;           float cc = b2 ? a1 : a0; const float dd = b2 ? a0 : a1; \
;           cc += dppf<0x141>(dd); cc += dppf<0xB1>(cc); cc += dppf<0x4E>(cc); dst = cc; }
; __device__ __forceinline__ void phase_scan(KP p) {
;     ...
;         SLD(A, 0); SLD(B, 1);
;         for (int g = 0; g < 8; ++g) {
;           const int st = g * 4;
;           SLD(C, st + 2); vnext = *(const float4*)(vb4 + st + 4);
;           __builtin_amdgcn_sched_barrier(0);
;           if (g > 0) { float yv; YRED4(yv); yb[(st - 4) * 16] = yv; }
;           SCOMP(A, vcur.x, q0);
;           SLD(D, st + 3);
;           __builtin_amdgcn_sched_barrier(0);
;           SCOMP(B, vcur.y, q1);
;           SLD(A, st + 4);
;           __builtin_amdgcn_sched_barrier(0);
;           SCOMP(C, vcur.z, q2);
;           SLD(B, st + 5);
;           __builtin_amdgcn_sched_barrier(0);
;           SCOMP(D, vcur.w, q3);
;           vcur = vnext; p0 = q0; p1 = q1; p2 = q2; p3 = q3;
;         }
;         { float yv; YRED4(yv); yb[28 * 16] = yv; }
	v_mfma_f32_32x32x16_bf16 v[20:35], v[112:115], v[124:127], 0
	v_add_f32_dpp v92, v92, v92 quad_perm:[2,3,0,1] row_mask:0xf bank_mask:0xf bound_ctrl:1
	v_add_f32_e32 v98, v90, v91
	v_add_f32_dpp v102, v102, v102 quad_perm:[2,3,0,1] row_mask:0xf bank_mask:0xf bound_ctrl:1
	v_add_f32_dpp v92, v92, v92 row_half_mirror row_mask:0xf bank_mask:0xf bound_ctrl:1
	ds_read_b128 v[36:39], v105 offset:27136
	s_nop 0
	v_add_f32_dpp v92, v92, v92 row_mirror row_mask:0xf bank_mask:0xf bound_ctrl:1
	ds_write_b32 v107, v102 offset:768
	v_pk_fma_f32 v[116:117], v[72:73], v[92:93], v[86:87] op_sel_hi:[1,0,1]
	v_pk_fma_f32 v[118:119], v[74:75], v[92:93], v[88:89] op_sel_hi:[1,0,1]
	s_waitcnt lgkmcnt(3)
	v_pk_mul_f32 v[84:85], v[116:117], v[8:9]
	v_pk_mul_f32 v[86:87], v[80:81], v[4:5] op_sel_hi:[0,1]
	v_pk_fma_f32 v[84:85], v[118:119], v[10:11], v[84:85]
	v_pk_mul_f32 v[88:89], v[80:81], v[6:7] op_sel_hi:[0,1]
	v_add_f32_e32 v92, v84, v85
	v_pk_fma_f32 v[86:87], v[116:117], v[16:17], v[86:87]
	v_pk_mul_f32 v[90:91], v[116:117], v[60:61]
	ds_read_b128 v[112:115], v128 offset:12512
	v_add_f32_dpp v92, v92, v92 quad_perm:[1,0,3,2] row_mask:0xf bank_mask:0xf bound_ctrl:1
	v_pk_fma_f32 v[88:89], v[118:119], v[18:19], v[88:89]
	v_pk_fma_f32 v[90:91], v[118:119], v[62:63], v[90:91]
	s_waitcnt lgkmcnt(3)
	v_mfma_f32_32x32x16_bf16 v[40:55], v[108:111], v[124:127], 0
	v_add_f32_dpp v92, v92, v92 quad_perm:[2,3,0,1] row_mask:0xf bank_mask:0xf bound_ctrl:1
	v_add_f32_e32 v99, v90, v91
	v_cndmask_b32_e64 v100, v98, v96, s[38:39]
	v_cndmask_b32_e64 v102, v96, v98, s[38:39]
	v_cndmask_b32_e64 v101, v99, v97, s[38:39]
	v_cndmask_b32_e64 v103, v97, v99, s[38:39]
	v_add_f32_dpp v92, v92, v92 row_half_mirror row_mask:0xf bank_mask:0xf bound_ctrl:1
	ds_read_b128 v[56:59], v105 offset:28416
	s_nop 0
	v_add_f32_dpp v92, v92, v92 row_mirror row_mask:0xf bank_mask:0xf bound_ctrl:1
	v_pk_fma_f32 v[116:117], v[12:13], v[92:93], v[86:87] op_sel_hi:[1,0,1]
	v_pk_fma_f32 v[118:119], v[14:15], v[92:93], v[88:89] op_sel_hi:[1,0,1]
	s_waitcnt lgkmcnt(3)
	v_pk_mul_f32 v[84:85], v[116:117], v[28:29]
	v_pk_mul_f32 v[86:87], v[80:81], v[24:25] op_sel:[1,0]
	v_pk_fma_f32 v[84:85], v[118:119], v[30:31], v[84:85]
	v_pk_mul_f32 v[88:89], v[80:81], v[26:27] op_sel:[1,0]
	v_add_f32_e32 v92, v84, v85
	v_pk_fma_f32 v[86:87], v[116:117], v[36:37], v[86:87]
	v_pk_mul_f32 v[90:91], v[116:117], v[0:1]
	ds_read_b128 v[108:111], v128 offset:13056
	v_add_f32_dpp v92, v92, v92 quad_perm:[1,0,3,2] row_mask:0xf bank_mask:0xf bound_ctrl:1
	v_pk_fma_f32 v[88:89], v[118:119], v[38:39], v[88:89]
	v_pk_fma_f32 v[90:91], v[118:119], v[2:3], v[90:91]
	s_waitcnt lgkmcnt(2)
	v_mfma_f32_32x32x16_bf16 v[60:75], v[112:115], v[124:127], 0
	v_add_f32_dpp v92, v92, v92 quad_perm:[2,3,0,1] row_mask:0xf bank_mask:0xf bound_ctrl:1
	v_add_f32_e32 v96, v90, v91
	v_add_f32_dpp v102, v102, v100 row_ror:8 row_mask:0xf bank_mask:0xf bound_ctrl:1
	v_add_f32_dpp v103, v103, v101 row_ror:8 row_mask:0xf bank_mask:0xf bound_ctrl:1
	v_add_f32_dpp v92, v92, v92 row_half_mirror row_mask:0xf bank_mask:0xf bound_ctrl:1
	ds_read_b128 v[76:79], v105 offset:29696
	s_nop 0
	v_add_f32_dpp v92, v92, v92 row_mirror row_mask:0xf bank_mask:0xf bound_ctrl:1
	v_cndmask_b32_e64 v104, v103, v102, s[40:41]
	v_cndmask_b32_e64 v102, v102, v103, s[40:41]
	v_pk_fma_f32 v[116:117], v[32:33], v[92:93], v[86:87] op_sel_hi:[1,0,1]
	v_pk_fma_f32 v[118:119], v[34:35], v[92:93], v[88:89] op_sel_hi:[1,0,1]
	s_waitcnt lgkmcnt(2)
	v_pk_mul_f32 v[84:85], v[116:117], v[48:49]
	v_pk_mul_f32 v[86:87], v[82:83], v[44:45] op_sel_hi:[0,1]
	v_pk_fma_f32 v[84:85], v[118:119], v[50:51], v[84:85]
	v_pk_mul_f32 v[88:89], v[82:83], v[46:47] op_sel_hi:[0,1]
	v_add_f32_e32 v92, v84, v85
	v_pk_fma_f32 v[86:87], v[116:117], v[56:57], v[86:87]
	v_pk_mul_f32 v[90:91], v[116:117], v[20:21]
	ds_read_b128 v[112:115], v128 offset:13600
	v_add_f32_dpp v92, v92, v92 quad_perm:[1,0,3,2] row_mask:0xf bank_mask:0xf bound_ctrl:1
	v_pk_fma_f32 v[88:89], v[118:119], v[58:59], v[88:89]
	v_pk_fma_f32 v[90:91], v[118:119], v[22:23], v[90:91]
	s_waitcnt lgkmcnt(2)
	v_mfma_f32_32x32x16_bf16 v[0:15], v[108:111], v[124:127], 0
	v_add_f32_dpp v92, v92, v92 quad_perm:[2,3,0,1] row_mask:0xf bank_mask:0xf bound_ctrl:1
	v_add_f32_e32 v97, v90, v91
	v_add_f32_dpp v102, v102, v104 row_half_mirror row_mask:0xf bank_mask:0xf bound_ctrl:1
	v_add_f32_dpp v92, v92, v92 row_half_mirror row_mask:0xf bank_mask:0xf bound_ctrl:1
	ds_read_b128 v[16:19], v105 offset:30976
	s_nop 0
	v_add_f32_dpp v92, v92, v92 row_mirror row_mask:0xf bank_mask:0xf bound_ctrl:1
	v_add_f32_dpp v102, v102, v102 quad_perm:[1,0,3,2] row_mask:0xf bank_mask:0xf bound_ctrl:1
	v_pk_fma_f32 v[116:117], v[52:53], v[92:93], v[86:87] op_sel_hi:[1,0,1]
	v_pk_fma_f32 v[118:119], v[54:55], v[92:93], v[88:89] op_sel_hi:[1,0,1]
	s_waitcnt lgkmcnt(2)
	v_pk_mul_f32 v[84:85], v[116:117], v[68:69]
	v_pk_mul_f32 v[86:87], v[82:83], v[64:65] op_sel:[1,0]
	v_pk_fma_f32 v[84:85], v[118:119], v[70:71], v[84:85]
	v_pk_mul_f32 v[88:89], v[82:83], v[66:67] op_sel:[1,0]
	ds_read_b128 v[80:83], v106 offset:96
	v_add_f32_e32 v92, v84, v85
	v_pk_fma_f32 v[86:87], v[116:117], v[76:77], v[86:87]
	v_pk_mul_f32 v[90:91], v[116:117], v[40:41]
	ds_read_b128 v[108:111], v128 offset:14144
	v_add_f32_dpp v92, v92, v92 quad_perm:[1,0,3,2] row_mask:0xf bank_mask:0xf bound_ctrl:1
	v_pk_fma_f32 v[88:89], v[118:119], v[78:79], v[88:89]
	v_pk_fma_f32 v[90:91], v[118:119], v[42:43], v[90:91]
	s_waitcnt lgkmcnt(3)
; #define YRED4(dst) { \
;           float a0 = b3 ? p2 : p0, a1 = b3 ? p3 : p1; const float s0 = b3 ? p0 : p2, s1 = b3 ? p1 : p3; \
;           a0 += dppf<0x128>(s0); a1 += dppf<0x128>(s1); \
;           float cc = b2 ? a1 : a0; const float dd = b2 ? a0 : a1; \
;           cc += dppf<0x141>(dd); cc += dppf<0xB1>(cc); cc += dppf<0x4E>(cc); dst = cc; }
; __device__ __forceinline__ void phase_scan(KP p) {
;     ...
;         SLD(A, 0); SLD(B, 1);
;         for (int g = 0; g < 8; ++g) {
;           const int st = g * 4;
;           SLD(C, st + 2); vnext = *(const float4*)(vb4 + st + 4);
;           __builtin_amdgcn_sched_barrier(0);
;           if (g > 0) { float yv; YRED4(yv); yb[(st - 4) * 16] = yv; }
;           SCOMP(A, vcur.x, q0);
;           SLD(D, st + 3);
;           __builtin_amdgcn_sched_barrier(0);
;           SCOMP(B, vcur.y, q1);
;           SLD(A, st + 4);
;           __builtin_amdgcn_sched_barrier(0);
;           SCOMP(C, vcur.z, q2);
;           SLD(B, st + 5);
;           __builtin_amdgcn_sched_barrier(0);
;           SCOMP(D, vcur.w, q3);
;           vcur = vnext; p0 = q0; p1 = q1; p2 = q2; p3 = q3;
;         }
;         { float yv; YRED4(yv); yb[28 * 16] = yv; }
	v_mfma_f32_32x32x16_bf16 v[20:35], v[112:115], v[124:127], 0
	v_add_f32_dpp v92, v92, v92 quad_perm:[2,3,0,1] row_mask:0xf bank_mask:0xf bound_ctrl:1
	v_add_f32_e32 v98, v90, v91
	v_add_f32_dpp v102, v102, v102 quad_perm:[2,3,0,1] row_mask:0xf bank_mask:0xf bound_ctrl:1
	v_add_f32_dpp v92, v92, v92 row_half_mirror row_mask:0xf bank_mask:0xf bound_ctrl:1
	ds_read_b128 v[36:39], v105 offset:32256
	s_nop 0
	v_add_f32_dpp v92, v92, v92 row_mirror row_mask:0xf bank_mask:0xf bound_ctrl:1
	ds_write_b32 v107, v102 offset:1024
	v_pk_fma_f32 v[116:117], v[72:73], v[92:93], v[86:87] op_sel_hi:[1,0,1]
	v_pk_fma_f32 v[118:119], v[74:75], v[92:93], v[88:89] op_sel_hi:[1,0,1]
	s_waitcnt lgkmcnt(3)
	v_pk_mul_f32 v[84:85], v[116:117], v[8:9]
	v_pk_mul_f32 v[86:87], v[80:81], v[4:5] op_sel_hi:[0,1]
	v_pk_fma_f32 v[84:85], v[118:119], v[10:11], v[84:85]
	v_pk_mul_f32 v[88:89], v[80:81], v[6:7] op_sel_hi:[0,1]
	v_add_f32_e32 v92, v84, v85
	v_pk_fma_f32 v[86:87], v[116:117], v[16:17], v[86:87]
	v_pk_mul_f32 v[90:91], v[116:117], v[60:61]
	ds_read_b128 v[112:115], v128 offset:14688
	v_add_f32_dpp v92, v92, v92 quad_perm:[1,0,3,2] row_mask:0xf bank_mask:0xf bound_ctrl:1
	v_pk_fma_f32 v[88:89], v[118:119], v[18:19], v[88:89]
	v_pk_fma_f32 v[90:91], v[118:119], v[62:63], v[90:91]
	s_waitcnt lgkmcnt(3)
	v_mfma_f32_32x32x16_bf16 v[40:55], v[108:111], v[124:127], 0
	v_add_f32_dpp v92, v92, v92 quad_perm:[2,3,0,1] row_mask:0xf bank_mask:0xf bound_ctrl:1
	v_add_f32_e32 v99, v90, v91
	v_cndmask_b32_e64 v100, v98, v96, s[38:39]
	v_cndmask_b32_e64 v102, v96, v98, s[38:39]
	v_cndmask_b32_e64 v101, v99, v97, s[38:39]
	v_cndmask_b32_e64 v103, v97, v99, s[38:39]
	v_add_f32_dpp v92, v92, v92 row_half_mirror row_mask:0xf bank_mask:0xf bound_ctrl:1
	ds_read_b128 v[56:59], v105 offset:33536
	s_nop 0
	v_add_f32_dpp v92, v92, v92 row_mirror row_mask:0xf bank_mask:0xf bound_ctrl:1
	v_pk_fma_f32 v[116:117], v[12:13], v[92:93], v[86:87] op_sel_hi:[1,0,1]
	v_pk_fma_f32 v[118:119], v[14:15], v[92:93], v[88:89] op_sel_hi:[1,0,1]
	s_waitcnt lgkmcnt(3)
	v_pk_mul_f32 v[84:85], v[116:117], v[28:29]
	v_pk_mul_f32 v[86:87], v[80:81], v[24:25] op_sel:[1,0]
	v_pk_fma_f32 v[84:85], v[118:119], v[30:31], v[84:85]
	v_pk_mul_f32 v[88:89], v[80:81], v[26:27] op_sel:[1,0]
	v_add_f32_e32 v92, v84, v85
	v_pk_fma_f32 v[86:87], v[116:117], v[36:37], v[86:87]
	v_pk_mul_f32 v[90:91], v[116:117], v[0:1]
	ds_read_b128 v[108:111], v128 offset:15232
	v_add_f32_dpp v92, v92, v92 quad_perm:[1,0,3,2] row_mask:0xf bank_mask:0xf bound_ctrl:1
	v_pk_fma_f32 v[88:89], v[118:119], v[38:39], v[88:89]
	v_pk_fma_f32 v[90:91], v[118:119], v[2:3], v[90:91]
	s_waitcnt lgkmcnt(2)
	v_mfma_f32_32x32x16_bf16 v[60:75], v[112:115], v[124:127], 0
	v_add_f32_dpp v92, v92, v92 quad_perm:[2,3,0,1] row_mask:0xf bank_mask:0xf bound_ctrl:1
	v_add_f32_e32 v96, v90, v91
	v_add_f32_dpp v102, v102, v100 row_ror:8 row_mask:0xf bank_mask:0xf bound_ctrl:1
	v_add_f32_dpp v103, v103, v101 row_ror:8 row_mask:0xf bank_mask:0xf bound_ctrl:1
	v_add_f32_dpp v92, v92, v92 row_half_mirror row_mask:0xf bank_mask:0xf bound_ctrl:1
	ds_read_b128 v[76:79], v105 offset:34816
	s_nop 0
	v_add_f32_dpp v92, v92, v92 row_mirror row_mask:0xf bank_mask:0xf bound_ctrl:1
	v_cndmask_b32_e64 v104, v103, v102, s[40:41]
	v_cndmask_b32_e64 v102, v102, v103, s[40:41]
	v_pk_fma_f32 v[116:117], v[32:33], v[92:93], v[86:87] op_sel_hi:[1,0,1]
	v_pk_fma_f32 v[118:119], v[34:35], v[92:93], v[88:89] op_sel_hi:[1,0,1]
	s_waitcnt lgkmcnt(2)
	v_pk_mul_f32 v[84:85], v[116:117], v[48:49]
	v_pk_mul_f32 v[86:87], v[82:83], v[44:45] op_sel_hi:[0,1]
	v_pk_fma_f32 v[84:85], v[118:119], v[50:51], v[84:85]
	v_pk_mul_f32 v[88:89], v[82:83], v[46:47] op_sel_hi:[0,1]
	v_add_f32_e32 v92, v84, v85
	v_pk_fma_f32 v[86:87], v[116:117], v[56:57], v[86:87]
	v_pk_mul_f32 v[90:91], v[116:117], v[20:21]
	ds_read_b128 v[112:115], v128 offset:15776
	v_add_f32_dpp v92, v92, v92 quad_perm:[1,0,3,2] row_mask:0xf bank_mask:0xf bound_ctrl:1
	v_pk_fma_f32 v[88:89], v[118:119], v[58:59], v[88:89]
	v_pk_fma_f32 v[90:91], v[118:119], v[22:23], v[90:91]
	s_waitcnt lgkmcnt(2)
	v_mfma_f32_32x32x16_bf16 v[0:15], v[108:111], v[124:127], 0
	v_add_f32_dpp v92, v92, v92 quad_perm:[2,3,0,1] row_mask:0xf bank_mask:0xf bound_ctrl:1
	v_add_f32_e32 v97, v90, v91
	v_add_f32_dpp v102, v102, v104 row_half_mirror row_mask:0xf bank_mask:0xf bound_ctrl:1
	v_add_f32_dpp v92, v92, v92 row_half_mirror row_mask:0xf bank_mask:0xf bound_ctrl:1
	ds_read_b128 v[16:19], v105 offset:36096
	s_nop 0
	v_add_f32_dpp v92, v92, v92 row_mirror row_mask:0xf bank_mask:0xf bound_ctrl:1
	v_add_f32_dpp v102, v102, v102 quad_perm:[1,0,3,2] row_mask:0xf bank_mask:0xf bound_ctrl:1
	v_pk_fma_f32 v[116:117], v[52:53], v[92:93], v[86:87] op_sel_hi:[1,0,1]
	v_pk_fma_f32 v[118:119], v[54:55], v[92:93], v[88:89] op_sel_hi:[1,0,1]
	s_waitcnt lgkmcnt(2)
	v_pk_mul_f32 v[84:85], v[116:117], v[68:69]
	v_pk_mul_f32 v[86:87], v[82:83], v[64:65] op_sel:[1,0]
	v_pk_fma_f32 v[84:85], v[118:119], v[70:71], v[84:85]
	v_pk_mul_f32 v[88:89], v[82:83], v[66:67] op_sel:[1,0]
	ds_read_b128 v[80:83], v106 offset:112
	v_add_f32_e32 v92, v84, v85
	v_pk_fma_f32 v[86:87], v[116:117], v[76:77], v[86:87]
	v_pk_mul_f32 v[90:91], v[116:117], v[40:41]
	ds_read_b128 v[108:111], v128 offset:16320
	v_add_f32_dpp v92, v92, v92 quad_perm:[1,0,3,2] row_mask:0xf bank_mask:0xf bound_ctrl:1
	v_pk_fma_f32 v[88:89], v[118:119], v[78:79], v[88:89]
	v_pk_fma_f32 v[90:91], v[118:119], v[42:43], v[90:91]
	s_waitcnt lgkmcnt(3)
; #define YRED4(dst) { \
;           float a0 = b3 ? p2 : p0, a1 = b3 ? p3 : p1; const float s0 = b3 ? p0 : p2, s1 = b3 ? p1 : p3; \
;           a0 += dppf<0x128>(s0); a1 += dppf<0x128>(s1); \
;           float cc = b2 ? a1 : a0; const float dd = b2 ? a0 : a1; \
;           cc += dppf<0x141>(dd); cc += dppf<0xB1>(cc); cc += dppf<0x4E>(cc); dst = cc; }
; __device__ __forceinline__ void phase_scan(KP p) {
;     ...
;         SLD(A, 0); SLD(B, 1);
;         for (int g = 0; g < 8; ++g) {
;           const int st = g * 4;
;           SLD(C, st + 2); vnext = *(const float4*)(vb4 + st + 4);
;           __builtin_amdgcn_sched_barrier(0);
;           if (g > 0) { float yv; YRED4(yv); yb[(st - 4) * 16] = yv; }
;           SCOMP(A, vcur.x, q0);
;           SLD(D, st + 3);
;           __builtin_amdgcn_sched_barrier(0);
;           SCOMP(B, vcur.y, q1);
;           SLD(A, st + 4);
;           __builtin_amdgcn_sched_barrier(0);
;           SCOMP(C, vcur.z, q2);
;           SLD(B, st + 5);
;           __builtin_amdgcn_sched_barrier(0);
;           SCOMP(D, vcur.w, q3);
;           vcur = vnext; p0 = q0; p1 = q1; p2 = q2; p3 = q3;
;         }
;         { float yv; YRED4(yv); yb[28 * 16] = yv; }
	v_mfma_f32_32x32x16_bf16 v[20:35], v[112:115], v[124:127], 0
	v_add_f32_dpp v92, v92, v92 quad_perm:[2,3,0,1] row_mask:0xf bank_mask:0xf bound_ctrl:1
	v_add_f32_e32 v98, v90, v91
	v_add_f32_dpp v102, v102, v102 quad_perm:[2,3,0,1] row_mask:0xf bank_mask:0xf bound_ctrl:1
	v_add_f32_dpp v92, v92, v92 row_half_mirror row_mask:0xf bank_mask:0xf bound_ctrl:1
	ds_read_b128 v[36:39], v105 offset:37376
	s_nop 0
	v_add_f32_dpp v92, v92, v92 row_mirror row_mask:0xf bank_mask:0xf bound_ctrl:1
	ds_write_b32 v107, v102 offset:1280
	v_pk_fma_f32 v[116:117], v[72:73], v[92:93], v[86:87] op_sel_hi:[1,0,1]
	v_pk_fma_f32 v[118:119], v[74:75], v[92:93], v[88:89] op_sel_hi:[1,0,1]
	s_waitcnt lgkmcnt(3)
	v_pk_mul_f32 v[84:85], v[116:117], v[8:9]
	v_pk_mul_f32 v[86:87], v[80:81], v[4:5] op_sel_hi:[0,1]
	v_pk_fma_f32 v[84:85], v[118:119], v[10:11], v[84:85]
	v_pk_mul_f32 v[88:89], v[80:81], v[6:7] op_sel_hi:[0,1]
	v_add_f32_e32 v92, v84, v85
	v_pk_fma_f32 v[86:87], v[116:117], v[16:17], v[86:87]
	v_pk_mul_f32 v[90:91], v[116:117], v[60:61]
	ds_read_b128 v[112:115], v128 offset:16864
	v_add_f32_dpp v92, v92, v92 quad_perm:[1,0,3,2] row_mask:0xf bank_mask:0xf bound_ctrl:1
	v_pk_fma_f32 v[88:89], v[118:119], v[18:19], v[88:89]
	v_pk_fma_f32 v[90:91], v[118:119], v[62:63], v[90:91]
	s_waitcnt lgkmcnt(3)
	v_mfma_f32_32x32x16_bf16 v[40:55], v[108:111], v[124:127], 0
	v_add_f32_dpp v92, v92, v92 quad_perm:[2,3,0,1] row_mask:0xf bank_mask:0xf bound_ctrl:1
	v_add_f32_e32 v99, v90, v91
	v_cndmask_b32_e64 v100, v98, v96, s[38:39]
	v_cndmask_b32_e64 v102, v96, v98, s[38:39]
	v_cndmask_b32_e64 v101, v99, v97, s[38:39]
	v_cndmask_b32_e64 v103, v97, v99, s[38:39]
	v_add_f32_dpp v92, v92, v92 row_half_mirror row_mask:0xf bank_mask:0xf bound_ctrl:1
	ds_read_b128 v[56:59], v105 offset:38656
	s_nop 0
	v_add_f32_dpp v92, v92, v92 row_mirror row_mask:0xf bank_mask:0xf bound_ctrl:1
	v_pk_fma_f32 v[116:117], v[12:13], v[92:93], v[86:87] op_sel_hi:[1,0,1]
	v_pk_fma_f32 v[118:119], v[14:15], v[92:93], v[88:89] op_sel_hi:[1,0,1]
	s_waitcnt lgkmcnt(3)
	v_pk_mul_f32 v[84:85], v[116:117], v[28:29]
	v_pk_mul_f32 v[86:87], v[80:81], v[24:25] op_sel:[1,0]
	v_pk_fma_f32 v[84:85], v[118:119], v[30:31], v[84:85]
	v_pk_mul_f32 v[88:89], v[80:81], v[26:27] op_sel:[1,0]
	v_add_f32_e32 v92, v84, v85
	v_pk_fma_f32 v[86:87], v[116:117], v[36:37], v[86:87]
	v_pk_mul_f32 v[90:91], v[116:117], v[0:1]
	v_add_f32_dpp v92, v92, v92 quad_perm:[1,0,3,2] row_mask:0xf bank_mask:0xf bound_ctrl:1
	v_pk_fma_f32 v[88:89], v[118:119], v[38:39], v[88:89]
	v_pk_fma_f32 v[90:91], v[118:119], v[2:3], v[90:91]
	s_waitcnt lgkmcnt(1)
	v_mfma_f32_32x32x16_bf16 v[60:75], v[112:115], v[124:127], 0
	v_add_f32_dpp v92, v92, v92 quad_perm:[2,3,0,1] row_mask:0xf bank_mask:0xf bound_ctrl:1
	v_add_f32_e32 v96, v90, v91
	v_add_f32_dpp v102, v102, v100 row_ror:8 row_mask:0xf bank_mask:0xf bound_ctrl:1
	v_add_f32_dpp v103, v103, v101 row_ror:8 row_mask:0xf bank_mask:0xf bound_ctrl:1
	v_add_f32_dpp v92, v92, v92 row_half_mirror row_mask:0xf bank_mask:0xf bound_ctrl:1
	ds_read_b128 v[76:79], v105 offset:39936
	s_nop 0
	v_add_f32_dpp v92, v92, v92 row_mirror row_mask:0xf bank_mask:0xf bound_ctrl:1
	v_cndmask_b32_e64 v104, v103, v102, s[40:41]
	v_cndmask_b32_e64 v102, v102, v103, s[40:41]
	v_pk_fma_f32 v[116:117], v[32:33], v[92:93], v[86:87] op_sel_hi:[1,0,1]
	v_pk_fma_f32 v[118:119], v[34:35], v[92:93], v[88:89] op_sel_hi:[1,0,1]
	s_waitcnt lgkmcnt(1)
	v_pk_mul_f32 v[84:85], v[116:117], v[48:49]
	v_pk_mul_f32 v[86:87], v[82:83], v[44:45] op_sel_hi:[0,1]
	v_pk_fma_f32 v[84:85], v[118:119], v[50:51], v[84:85]
	v_pk_mul_f32 v[88:89], v[82:83], v[46:47] op_sel_hi:[0,1]
	v_add_f32_e32 v92, v84, v85
	v_pk_fma_f32 v[86:87], v[116:117], v[56:57], v[86:87]
	v_pk_mul_f32 v[90:91], v[116:117], v[20:21]
	v_add_f32_dpp v92, v92, v92 quad_perm:[1,0,3,2] row_mask:0xf bank_mask:0xf bound_ctrl:1
	v_pk_fma_f32 v[88:89], v[118:119], v[58:59], v[88:89]
	v_pk_fma_f32 v[90:91], v[118:119], v[22:23], v[90:91]
	v_add_f32_dpp v92, v92, v92 quad_perm:[2,3,0,1] row_mask:0xf bank_mask:0xf bound_ctrl:1
	v_add_f32_e32 v97, v90, v91
	v_add_f32_dpp v102, v102, v104 row_half_mirror row_mask:0xf bank_mask:0xf bound_ctrl:1
	v_add_f32_dpp v92, v92, v92 row_half_mirror row_mask:0xf bank_mask:0xf bound_ctrl:1
	s_nop 1
	v_add_f32_dpp v92, v92, v92 row_mirror row_mask:0xf bank_mask:0xf bound_ctrl:1
	v_add_f32_dpp v102, v102, v102 quad_perm:[1,0,3,2] row_mask:0xf bank_mask:0xf bound_ctrl:1
	v_pk_fma_f32 v[116:117], v[52:53], v[92:93], v[86:87] op_sel_hi:[1,0,1]
	v_pk_fma_f32 v[118:119], v[54:55], v[92:93], v[88:89] op_sel_hi:[1,0,1]
	s_waitcnt lgkmcnt(0)
	v_pk_mul_f32 v[84:85], v[116:117], v[68:69]
	v_pk_mul_f32 v[86:87], v[82:83], v[64:65] op_sel:[1,0]
	v_pk_fma_f32 v[84:85], v[118:119], v[70:71], v[84:85]
	v_pk_mul_f32 v[88:89], v[82:83], v[66:67] op_sel:[1,0]
	v_add_f32_e32 v92, v84, v85
	v_pk_fma_f32 v[86:87], v[116:117], v[76:77], v[86:87]
	v_pk_mul_f32 v[90:91], v[116:117], v[40:41]
	v_add_f32_dpp v92, v92, v92 quad_perm:[1,0,3,2] row_mask:0xf bank_mask:0xf bound_ctrl:1
	v_pk_fma_f32 v[88:89], v[118:119], v[78:79], v[88:89]
	v_pk_fma_f32 v[90:91], v[118:119], v[42:43], v[90:91]
	v_add_f32_dpp v92, v92, v92 quad_perm:[2,3,0,1] row_mask:0xf bank_mask:0xf bound_ctrl:1
	v_add_f32_e32 v98, v90, v91
	v_add_f32_dpp v102, v102, v102 quad_perm:[2,3,0,1] row_mask:0xf bank_mask:0xf bound_ctrl:1
	v_add_f32_dpp v92, v92, v92 row_half_mirror row_mask:0xf bank_mask:0xf bound_ctrl:1
	s_nop 1
	v_add_f32_dpp v92, v92, v92 row_mirror row_mask:0xf bank_mask:0xf bound_ctrl:1
	ds_write_b32 v107, v102 offset:1536
	v_pk_fma_f32 v[116:117], v[72:73], v[92:93], v[86:87] op_sel_hi:[1,0,1]
	v_pk_fma_f32 v[118:119], v[74:75], v[92:93], v[88:89] op_sel_hi:[1,0,1]
	v_cndmask_b32_e64 v100, v98, v96, s[38:39]
	v_pk_mul_f32 v[90:91], v[116:117], v[60:61]
	v_cndmask_b32_e64 v102, v96, v98, s[38:39]
	v_pk_fma_f32 v[90:91], v[118:119], v[62:63], v[90:91]
	s_nop 0
	v_add_f32_e32 v99, v90, v91
	v_add_f32_dpp v102, v102, v100 row_ror:8 row_mask:0xf bank_mask:0xf bound_ctrl:1
	v_cndmask_b32_e64 v101, v99, v97, s[38:39]
	v_cndmask_b32_e64 v103, v97, v99, s[38:39]
	s_nop 1
	v_add_f32_dpp v103, v103, v101 row_ror:8 row_mask:0xf bank_mask:0xf bound_ctrl:1
	v_cndmask_b32_e64 v104, v103, v102, s[40:41]
	v_cndmask_b32_e64 v102, v102, v103, s[40:41]
	s_nop 1
	v_add_f32_dpp v102, v102, v104 row_half_mirror row_mask:0xf bank_mask:0xf bound_ctrl:1
	s_nop 1
	v_add_f32_dpp v102, v102, v102 quad_perm:[1,0,3,2] row_mask:0xf bank_mask:0xf bound_ctrl:1
	s_nop 1
	v_add_f32_dpp v102, v102, v102 quad_perm:[2,3,0,1] row_mask:0xf bank_mask:0xf bound_ctrl:1
	ds_write_b32 v107, v102 offset:1792
	s_branch .LBB0_755
